# grid barrier: last XCD leader fans the release out to every XCC generation word itself (no TOPGEN->leader->XGEN hop); other leaders wait on their own XCC word
# baseline (speedup 1.0000x reference)
; __device__ __forceinline__ unsigned xb_ld(unsigned* p)              { return __hip_atomic_load(p, __ATOMIC_RELAXED, __HIP_MEMORY_SCOPE_AGENT); }
; __device__ __forceinline__ unsigned xb_add(unsigned* p, unsigned v) { return __hip_atomic_fetch_add(p, v, __ATOMIC_RELAXED, __HIP_MEMORY_SCOPE_AGENT); }
; #define XB_SPIN(cond, bar) do { unsigned _sp = 0; while (cond) { __builtin_amdgcn_s_sleep(1); \
;     if ((++_sp & 255u) == 0u) { if (xb_ld(&(bar)[XB_TMO])) break; if (_sp > XB_SPIN_CAP) { atomicAdd(&(bar)[XB_TMO], 1u); break; } } } } while (0)
; __device__ __forceinline__ void xcd_barrier(const XcdBarrier& b) {
;     ...
;         if (old + 1u == (gen + 1u) * nloc) {
;             __builtin_amdgcn_fence(__ATOMIC_RELEASE, "agent");
;             asm volatile("s_waitcnt vmcnt(0)" ::: "memory");
;             const unsigned og = xb_add(&bar[XB_TOP], 1u);
;             const unsigned tg = og / nx;
;             if (og + 1u == (tg + 1u) * nx) xb_add(&bar[XB_TOPGEN], 1u);
;             else XB_SPIN(xb_ld(&bar[XB_TOPGEN]) == tg, bar);
;             __builtin_amdgcn_fence(__ATOMIC_ACQUIRE, "agent");
;             xb_add(&bar[XB_XGEN(b.x)], 1u);
;             asm volatile("s_waitcnt vmcnt(0)" ::: "memory");
.LBB0_1041:
	s_andn2_saveexec_b64 s[2:3], s[2:3]
	s_cbranch_execz .LBB0_1061
	v_mov_b32_e32 v7, v0
	s_mov_b64 s[2:3], exec
	buffer_wbl2 sc1
	s_waitcnt lgkmcnt(0)
	s_waitcnt vmcnt(0)
	buffer_inv sc1
	v_mbcnt_lo_u32_b32 v0, s2, 0
	v_mbcnt_hi_u32_b32 v0, s3, v0
	v_cmp_eq_u32_e32 vcc, 0, v0
	s_and_saveexec_b64 s[4:5], vcc
	s_cbranch_execz .LBB0_1044
	s_bcnt1_i32_b64 s2, s[2:3]
	v_mov_b32_e32 v3, s2
	v_readlane_b32 s2, v252, 5
	v_readlane_b32 s3, v252, 6
	s_nop 4
	global_atomic_add v3, v1, v3, s[2:3] sc0
.LBB0_1044:
	s_or_b64 exec, exec, s[4:5]
	s_waitcnt vmcnt(0)
	v_readfirstlane_b32 s2, v3
	v_sub_u32_e32 v4, 0, v2
	s_mov_b64 s[4:5], -1
	v_add_u32_e32 v3, s2, v0
	v_cvt_f32_u32_e32 v0, v2
	v_readlane_b32 s2, v252, 7
	v_readlane_b32 s3, v252, 8
	v_rcp_iflag_f32_e32 v0, v0
	s_nop 0
	v_mul_f32_e32 v0, 0x4f7ffffe, v0
	v_cvt_u32_f32_e32 v0, v0
	v_mul_lo_u32 v4, v4, v0
	v_mul_hi_u32 v4, v0, v4
	v_add_u32_e32 v0, v0, v4
	v_mul_hi_u32 v0, v3, v0
	v_mul_lo_u32 v4, v0, v2
	v_sub_u32_e32 v4, v3, v4
	v_cmp_ge_u32_e32 vcc, v4, v2
	v_add_u32_e32 v5, 1, v0
	v_add_u32_e32 v3, 1, v3
	v_cndmask_b32_e32 v0, v0, v5, vcc
	v_sub_u32_e32 v5, v4, v2
	v_cndmask_b32_e32 v4, v4, v5, vcc
	v_cmp_ge_u32_e32 vcc, v4, v2
	v_add_u32_e32 v4, 1, v0
	s_nop 0
	v_cndmask_b32_e32 v0, v0, v4, vcc
	v_mul_lo_u32 v4, v2, v0
	v_add_u32_e32 v2, v4, v2
	v_cmp_ne_u32_e32 vcc, v3, v2
	v_mov_b64_e32 v[2:3], s[2:3]
	s_and_saveexec_b64 s[2:3], vcc
	s_cbranch_execz .LBB0_1056
	v_readlane_b32 s4, v252, 3
	v_readlane_b32 s5, v252, 4
	s_mov_b64 s[6:7], 0
	s_nop 3
	global_load_dword v2, v1, s[4:5] sc1
	s_waitcnt vmcnt(0)
	v_cmp_eq_u32_e32 vcc, v2, v7
	s_and_saveexec_b64 s[4:5], vcc
	s_cbranch_execz .LBB0_1055
	s_mov_b32 s17, 1
	s_branch .LBB0_1048

; __device__ __forceinline__ unsigned xb_ld(unsigned* p)              { return __hip_atomic_load(p, __ATOMIC_RELAXED, __HIP_MEMORY_SCOPE_AGENT); }
; __device__ __forceinline__ unsigned xb_add(unsigned* p, unsigned v) { return __hip_atomic_fetch_add(p, v, __ATOMIC_RELAXED, __HIP_MEMORY_SCOPE_AGENT); }
; #define XB_SPIN(cond, bar) do { unsigned _sp = 0; while (cond) { __builtin_amdgcn_s_sleep(1); \
;     if ((++_sp & 255u) == 0u) { if (xb_ld(&(bar)[XB_TMO])) break; if (_sp > XB_SPIN_CAP) { atomicAdd(&(bar)[XB_TMO], 1u); break; } } } } while (0)
; __device__ __forceinline__ void xcd_barrier(const XcdBarrier& b) {
;     ...
;             else XB_SPIN(xb_ld(&bar[XB_TOPGEN]) == tg, bar);
;             __builtin_amdgcn_fence(__ATOMIC_ACQUIRE, "agent");
;             xb_add(&bar[XB_XGEN(b.x)], 1u);
;             asm volatile("s_waitcnt vmcnt(0)" ::: "memory");
;         } else {
;             XB_SPIN(xb_ld(&bar[XB_XGEN(b.x)]) == gen, bar);
.LBB0_1050:
	v_readlane_b32 s10, v252, 3
	v_readlane_b32 s11, v252, 4
	s_add_i32 s17, s17, 1
	s_mov_b64 s[12:13], -1
	s_nop 2
	global_load_dword v2, v1, s[10:11] sc1
	s_waitcnt vmcnt(0)
	v_cmp_ne_u32_e32 vcc, v2, v7
	s_orn2_b64 s[10:11], vcc, exec
	s_branch .LBB0_1047

; __device__ __forceinline__ unsigned xb_ld(unsigned* p)              { return __hip_atomic_load(p, __ATOMIC_RELAXED, __HIP_MEMORY_SCOPE_AGENT); }
; __device__ __forceinline__ unsigned xb_add(unsigned* p, unsigned v) { return __hip_atomic_fetch_add(p, v, __ATOMIC_RELAXED, __HIP_MEMORY_SCOPE_AGENT); }
; #define XB_SPIN(cond, bar) do { unsigned _sp = 0; while (cond) { __builtin_amdgcn_s_sleep(1); \
;     if ((++_sp & 255u) == 0u) { if (xb_ld(&(bar)[XB_TMO])) break; if (_sp > XB_SPIN_CAP) { atomicAdd(&(bar)[XB_TMO], 1u); break; } } } } while (0)
; __device__ __forceinline__ void xcd_barrier(const XcdBarrier& b) {
;     ...
;             const unsigned og = xb_add(&bar[XB_TOP], 1u);
;             const unsigned tg = og / nx;
;             if (og + 1u == (tg + 1u) * nx) xb_add(&bar[XB_TOPGEN], 1u);
;             else XB_SPIN(xb_ld(&bar[XB_TOPGEN]) == tg, bar);
;             __builtin_amdgcn_fence(__ATOMIC_ACQUIRE, "agent");
;             xb_add(&bar[XB_XGEN(b.x)], 1u);
;             asm volatile("s_waitcnt vmcnt(0)" ::: "memory");
.LBB0_1056:
	s_or_b64 exec, exec, s[2:3]
	s_and_saveexec_b64 s[2:3], s[4:5]
	s_cbranch_execz .LBB0_1058
	global_atomic_add v[2:3], v215, off
	v_readlane_b32 s6, v251, 7
	v_readlane_b32 s7, v251, 8
	v_mov_b32_e32 v8, 1
	s_nop 3
	s_add_u32 s6, s6, 0x2200
	s_addc_u32 s7, s7, 0
	s_nop 0
	global_atomic_add v1, v8, s[6:7]
	global_atomic_add v1, v8, s[6:7] offset:256
	global_atomic_add v1, v8, s[6:7] offset:512
	global_atomic_add v1, v8, s[6:7] offset:768
	global_atomic_add v1, v8, s[6:7] offset:1024
	global_atomic_add v1, v8, s[6:7] offset:1280
	global_atomic_add v1, v8, s[6:7] offset:1536
	global_atomic_add v1, v8, s[6:7] offset:1792
	global_atomic_add v1, v8, s[6:7] offset:2048
	global_atomic_add v1, v8, s[6:7] offset:2304
	global_atomic_add v1, v8, s[6:7] offset:2560
	global_atomic_add v1, v8, s[6:7] offset:2816
	global_atomic_add v1, v8, s[6:7] offset:3072
	global_atomic_add v1, v8, s[6:7] offset:3328
	global_atomic_add v1, v8, s[6:7] offset:3584
	global_atomic_add v1, v8, s[6:7] offset:3840
.LBB0_1058:
	s_or_b64 exec, exec, s[2:3]
	s_mov_b64 s[2:3], exec
	v_mbcnt_lo_u32_b32 v0, s2, 0
	v_mbcnt_hi_u32_b32 v0, s3, v0
	v_cmp_eq_u32_e32 vcc, 0, v0
	s_waitcnt vmcnt(0)
	s_and_saveexec_b64 s[4:5], vcc
	s_cbranch_execz .LBB0_1060
	s_bcnt1_i32_b64 s2, s[2:3]
	v_mov_b32_e32 v0, s2
	v_readlane_b32 s2, v252, 3
	v_readlane_b32 s3, v252, 4
	s_nop 4
.LBB0_1060:
	s_or_b64 exec, exec, s[4:5]
	s_waitcnt vmcnt(0)
